# dead spill-reload elimination: 35 SGPR reloads per key-conversion block (tile blocks 1-6) removed, the compact conversion no longer clobbers those registers
# speedup vs baseline: 1.0048x; 1.0048x over previous
; DI void a1_task(unsigned char* shm, const bf16_t* prm, const bf16_t* prt, unsigned* mask, int b, int qt, const int tid) {
;     ...
; #pragma unroll
;             for (int i = 0; i < 16; ++i) {
;                 const int s = s0 + 16 * (i >> 3) + 8 * h + (i & 7);
;                 const unsigned u = __float_as_uint(idx[i] + 0.0f);
;                 const unsigned k = (u & 0x80000000u) ? ~u : (u | 0x80000000u);
;                 key[jt][i] = (s <= t0 + r) ? k : 0u;
;             }
;             if (hn) {
; #pragma unroll
;                 for (int ks = 0; ks < 4; ++ks) kf[ks] = kn[ks];
;             }
;         } else {
; #pragma unroll
;             for (int i = 0; i < 16; ++i) key[jt][i] = 0u;
;         }
.LBB0_402:
	v_readlane_b32 s6, v255, 40
	s_mov_b64 s[96:97], 0x2c0000
	v_readlane_b32 s94, v254, 47
	v_readlane_b32 s95, v254, 48
	v_readlane_b32 s81, v254, 52
	v_readlane_b32 s94, v254, 61
	v_readlane_b32 s95, v254, 62
	v_readlane_b32 s81, v254, 1
	s_mov_b64 s[82:83], 0x58000
	v_readlane_b32 s7, v255, 41
	s_branch .LBB0_404

; DI void a1_task(unsigned char* shm, const bf16_t* prm, const bf16_t* prt, unsigned* mask, int b, int qt, const int tid) {
;     ...
; #pragma unroll
;             for (int i = 0; i < 16; ++i) {
;                 const int s = s0 + 16 * (i >> 3) + 8 * h + (i & 7);
;                 const unsigned u = __float_as_uint(idx[i] + 0.0f);
;                 const unsigned k = (u & 0x80000000u) ? ~u : (u | 0x80000000u);
;                 key[jt][i] = (s <= t0 + r) ? k : 0u;
;             }
;             if (hn) {
; #pragma unroll
;                 for (int ks = 0; ks < 4; ++ks) kf[ks] = kn[ks];
;             }
;         } else {
; #pragma unroll
;             for (int i = 0; i < 16; ++i) key[jt][i] = 0u;
;         }
.LBB0_411:
	s_mov_b64 s[96:97], 0x2c0000
	v_readlane_b32 s6, v255, 40
	v_readlane_b32 s94, v254, 47
	v_readlane_b32 s95, v254, 48
	v_readlane_b32 s81, v254, 52
	v_readlane_b32 s94, v254, 61
	s_mov_b64 s[0:1], 0
	v_readlane_b32 s95, v254, 62
	v_readlane_b32 s81, v254, 1
	s_mov_b64 s[82:83], 0x58000
	v_readlane_b32 s7, v255, 41

; DI void a1_task(unsigned char* shm, const bf16_t* prm, const bf16_t* prt, unsigned* mask, int b, int qt, const int tid) {
;     ...
; #pragma unroll
;             for (int i = 0; i < 16; ++i) {
;                 const int s = s0 + 16 * (i >> 3) + 8 * h + (i & 7);
;                 const unsigned u = __float_as_uint(idx[i] + 0.0f);
;                 const unsigned k = (u & 0x80000000u) ? ~u : (u | 0x80000000u);
;                 key[jt][i] = (s <= t0 + r) ? k : 0u;
;             }
;             if (hn) {
; #pragma unroll
;                 for (int ks = 0; ks < 4; ++ks) kf[ks] = kn[ks];
;             }
;         } else {
; #pragma unroll
;             for (int i = 0; i < 16; ++i) key[jt][i] = 0u;
;         }
.LBB0_431:
	s_mov_b64 s[96:97], 0x2c0000
	v_readlane_b32 s6, v255, 40
	v_readlane_b32 s94, v254, 47
	v_readlane_b32 s95, v254, 48
	v_readlane_b32 s81, v254, 52
	v_readlane_b32 s94, v254, 61
	s_mov_b64 s[0:1], 0
	v_readlane_b32 s95, v254, 62
	v_readlane_b32 s81, v254, 1
	s_mov_b64 s[82:83], 0x58000
	v_readlane_b32 s4, v255, 56
	v_readlane_b32 s7, v255, 41
	v_readlane_b32 s5, v255, 57

; DI void a1_task(unsigned char* shm, const bf16_t* prm, const bf16_t* prt, unsigned* mask, int b, int qt, const int tid) {
;     ...
; #pragma unroll
;             for (int i = 0; i < 16; ++i) {
;                 const int s = s0 + 16 * (i >> 3) + 8 * h + (i & 7);
;                 const unsigned u = __float_as_uint(idx[i] + 0.0f);
;                 const unsigned k = (u & 0x80000000u) ? ~u : (u | 0x80000000u);
;                 key[jt][i] = (s <= t0 + r) ? k : 0u;
;             }
;             if (hn) {
; #pragma unroll
;                 for (int ks = 0; ks < 4; ++ks) kf[ks] = kn[ks];
;             }
;         } else {
; #pragma unroll
;             for (int i = 0; i < 16; ++i) key[jt][i] = 0u;
;         }
.LBB0_441:
	s_mov_b64 s[96:97], 0x2c0000
	v_readlane_b32 s6, v255, 40
	v_readlane_b32 s94, v254, 47
	v_readlane_b32 s95, v254, 48
	v_readlane_b32 s81, v254, 52
	v_readlane_b32 s94, v254, 61
	s_mov_b64 s[0:1], 0
	v_readlane_b32 s95, v254, 62
	v_readlane_b32 s81, v254, 1
	s_mov_b64 s[82:83], 0x58000
	v_readlane_b32 s40, v255, 60
	v_readlane_b32 s7, v255, 41
	v_readlane_b32 s41, v255, 61

; DI void a1_task(unsigned char* shm, const bf16_t* prm, const bf16_t* prt, unsigned* mask, int b, int qt, const int tid) {
;     ...
; #pragma unroll
;             for (int i = 0; i < 16; ++i) {
;                 const int s = s0 + 16 * (i >> 3) + 8 * h + (i & 7);
;                 const unsigned u = __float_as_uint(idx[i] + 0.0f);
;                 const unsigned k = (u & 0x80000000u) ? ~u : (u | 0x80000000u);
;                 key[jt][i] = (s <= t0 + r) ? k : 0u;
;             }
;             if (hn) {
; #pragma unroll
;                 for (int ks = 0; ks < 4; ++ks) kf[ks] = kn[ks];
;             }
;         } else {
; #pragma unroll
;             for (int i = 0; i < 16; ++i) key[jt][i] = 0u;
;         }
.LBB0_451:
	s_mov_b64 s[96:97], 0x2c0000
	v_readlane_b32 s94, v254, 47
	v_readlane_b32 s95, v254, 48
	v_readlane_b32 s81, v254, 52
	v_readlane_b32 s94, v254, 61
	s_mov_b64 s[0:1], 0
	v_readlane_b32 s95, v254, 62
	v_readlane_b32 s81, v254, 1
	s_mov_b64 s[82:83], 0x58000
